# stage A next-item L2 prefetch by waves 4-7: dummy loads into a dedicated register and no vmcnt(0) wait before the barrier
# speedup vs baseline: 1.0098x; 1.0098x over previous
; __device__ __forceinline__ void chunkA_item(const Args& A, LAS unsigned char* lds, int tid, int lane, int wave, int ci, int ci_next, HeadConstA& H) {
;     ...
;     } else if (ci_next < 4096) {
;         const int cn = ci_next & 31, hn = (ci_next >> 5) & 7, bn = ci_next >> 8; const long rown = (long)bn * SEQ + cn * 64 - 1;
;         for (int l = tid - 256; l < 65 * 5; l += 256) { const int r = l / 5, sec = l % 5; long rr = rown + r; if (rr < 0) rr = 0;
;             const bf16_t* p = Z + rr * NZ + (sec == 0 ? hn * 64 : sec == 1 ? 512 + hn * 64 : sec == 2 ? 1024 + hn * 64 : sec == 3 ? 1536 : 1600);
;             unsigned dummy; asm volatile("global_load_dword %0, %1, off" : "=v"(dummy) : "v"(p) : "memory"); }
;         asm volatile("s_waitcnt vmcnt(0)" ::: "memory");
;     }
.LBB0_214:
	s_or_b64 exec, exec, s[24:25]
	v_lshl_add_u64 v[34:35], s[30:31], 0, v[72:73]
	v_cmp_lt_i64_e32 vcc, 0, v[34:35]
	s_nop 1
	v_cndmask_b32_e32 v33, 0, v35, vcc
	v_cndmask_b32_e32 v37, 0, v34, vcc
	v_mov_b64_e32 v[34:35], s[94:95]
	v_mad_u64_u32 v[34:35], s[24:25], v37, s22, v[34:35]
	v_mov_b32_e32 v38, v35
	v_mad_u64_u32 v[38:39], s[24:25], v33, s22, v[38:39]
	v_mov_b32_e32 v35, v38
	v_mov_b32_e32 v37, v73
	v_lshl_add_u64 v[34:35], v[36:37], 1, v[34:35]
	global_load_dword v186, v[34:35], off
	s_movk_i32 s24, 0x44
	v_add_u32_e32 v33, 0x100, v32
	v_cmp_lt_i32_e32 vcc, s24, v32
	s_or_b64 s[34:35], vcc, s[34:35]
	v_mov_b32_e32 v32, v33
	s_andn2_b64 exec, exec, s[34:35]
	s_cbranch_execz .LBB0_227

; #define LBAR() asm volatile("s_waitcnt lgkmcnt(0)\n\ts_barrier" ::: "memory")
; __device__ __forceinline__ void chunkA_item(const Args& A, LAS unsigned char* lds, int tid, int lane, int wave, int ci, int ci_next, HeadConstA& H) {
;     ...
;         asm volatile("s_waitcnt vmcnt(0)" ::: "memory");
;     }
;     LBAR();
.LBB0_227:
	s_or_b64 exec, exec, s[80:81]
	s_nop 0
